# P8a: touch-prefetch the 4 new U rows of the block's next prompt item into L2 at each W-path consumer wait (vmcnt(4) instead of vmcnt(0))
# baseline (speedup 1.0000x reference)
.LBB0_1644:
	s_and_b64 s[0:1], s[10:11], exec
	s_cselect_b32 s0, 1.0, 0.5
	v_mov_b32_e32 v24, s0
	s_add_i32 s98, s2, s92
	s_cmpk_lt_i32 s98, 0x800
	s_cbranch_scc0 .Lp8a_pf0_skip
	s_add_i32 s98, s18, s24
	s_lshl_b32 s98, s98, 13
	s_mov_b32 s99, 0
	v_lshl_add_u64 v[108:109], v[86:87], 0, s[98:99]
	s_add_u32 s98, s98, 0x2000
	v_lshl_add_u64 v[110:111], v[86:87], 0, s[98:99]
	s_add_u32 s98, s98, 0x2000
	v_lshl_add_u64 v[112:113], v[86:87], 0, s[98:99]
	s_add_u32 s98, s98, 0x2000
	v_lshl_add_u64 v[114:115], v[86:87], 0, s[98:99]
	global_load_dword v116, v[108:109], off
	global_load_dword v117, v[110:111], off
	global_load_dword v118, v[112:113], off
	global_load_dword v119, v[114:115], off
	s_waitcnt vmcnt(4)
	s_branch .Lp8a_pf0_done

.Lp8a_pf0_done:
	v_pk_add_f32 v[20:21], v[2:3], v[6:7]
	v_pk_add_f32 v[22:23], v[0:1], v[4:5]
	v_cndmask_b32_e64 v24, 0.5, v24, s[6:7]
	v_xor_b32_e32 v27, 0x80000000, v7
	v_xor_b32_e32 v26, 0x80000000, v6
	s_ashr_i32 s19, s18, 31
	v_pk_fma_f32 v[26:27], v[24:25], v[20:21], v[26:27] op_sel_hi:[0,1,1]
	v_pk_fma_f32 v[24:25], v[24:25], v[22:23], v[4:5] op_sel_hi:[0,1,1] neg_lo:[0,0,1] neg_hi:[0,0,1]
	s_lshl_b64 s[0:1], s[18:19], 12
	v_cvt_pk_bf16_f32 v24, v24, v25
	v_cvt_pk_bf16_f32 v25, v26, v27
	v_lshl_add_u64 v[26:27], v[96:97], 0, s[0:1]
	v_sub_f32_e32 v1, v9, v1
	v_sub_f32_e32 v0, v8, v0
	v_sub_f32_e32 v3, v11, v3
	v_sub_f32_e32 v2, v10, v2
	s_add_i32 s0, s18, 1
	v_pk_add_f32 v[2:3], v[20:21], v[2:3]
	v_pk_add_f32 v[0:1], v[22:23], v[0:1]
	v_xor_b32_e32 v21, 0x80000000, v11
	v_xor_b32_e32 v20, 0x80000000, v10
	s_ashr_i32 s1, s0, 31
	v_pk_fma_f32 v[20:21], v[2:3], 0.5, v[20:21] op_sel_hi:[1,0,1]
	v_pk_fma_f32 v[22:23], v[0:1], 0.5, v[8:9] op_sel_hi:[1,0,1] neg_lo:[0,0,1] neg_hi:[0,0,1]
	s_lshl_b64 s[0:1], s[0:1], 12
	v_cvt_pk_bf16_f32 v22, v22, v23
	v_cvt_pk_bf16_f32 v23, v20, v21
	v_lshl_add_u64 v[20:21], v[96:97], 0, s[0:1]
	v_sub_f32_e32 v7, v15, v7
	v_sub_f32_e32 v6, v14, v6
	v_sub_f32_e32 v5, v13, v5
	v_sub_f32_e32 v4, v12, v4
	s_add_i32 s0, s18, 2
	v_pk_add_f32 v[0:1], v[0:1], v[4:5]
	v_pk_add_f32 v[2:3], v[2:3], v[6:7]
	v_xor_b32_e32 v5, 0x80000000, v15
	v_xor_b32_e32 v4, 0x80000000, v14
	s_ashr_i32 s1, s0, 31
	v_pk_fma_f32 v[4:5], v[2:3], 0.5, v[4:5] op_sel_hi:[1,0,1]
	v_pk_fma_f32 v[6:7], v[0:1], 0.5, v[12:13] op_sel_hi:[1,0,1] neg_lo:[0,0,1] neg_hi:[0,0,1]
	s_lshl_b64 s[0:1], s[0:1], 12
	v_cvt_pk_bf16_f32 v6, v6, v7
	v_cvt_pk_bf16_f32 v7, v4, v5
	v_lshl_add_u64 v[4:5], v[96:97], 0, s[0:1]
	global_store_dwordx2 v[4:5], v[6:7], off
	v_sub_f32_e32 v5, v19, v11
	v_sub_f32_e32 v4, v18, v10
	v_sub_f32_e32 v7, v17, v9
	v_sub_f32_e32 v6, v16, v8
	v_pk_add_f32 v[0:1], v[0:1], v[6:7]
	v_pk_add_f32 v[2:3], v[2:3], v[4:5]
	v_xor_b32_e32 v5, 0x80000000, v19
	v_xor_b32_e32 v4, 0x80000000, v18
	v_pk_fma_f32 v[2:3], v[2:3], 0.5, v[4:5] op_sel_hi:[1,0,1]
	v_pk_fma_f32 v[0:1], v[0:1], 0.5, v[16:17] op_sel_hi:[1,0,1] neg_lo:[0,0,1] neg_hi:[0,0,1]
	v_mov_b64_e32 v[4:5], v[90:91]
	global_store_dwordx2 v[26:27], v[24:25], off
	global_store_dwordx2 v[20:21], v[22:23], off

.LBB0_1736:
	s_min_u32 s8, s20, 3
	s_add_i32 s8, s8, 1
	v_cvt_f32_ubyte0_e32 v32, s8
	v_div_scale_f32 v33, s[8:9], v32, v32, 1.0
	v_rcp_f32_e32 v34, v33
	s_add_i32 s98, s2, s92
	s_cmpk_lt_i32 s98, 0x800
	s_cbranch_scc0 .Lp8a_pf1_skip
	s_add_i32 s98, s18, s24
	s_lshl_b32 s98, s98, 13
	s_mov_b32 s99, 0
	v_lshl_add_u64 v[108:109], v[86:87], 0, s[98:99]
	s_add_u32 s98, s98, 0x2000
	v_lshl_add_u64 v[110:111], v[86:87], 0, s[98:99]
	s_add_u32 s98, s98, 0x2000
	v_lshl_add_u64 v[112:113], v[86:87], 0, s[98:99]
	s_add_u32 s98, s98, 0x2000
	v_lshl_add_u64 v[114:115], v[86:87], 0, s[98:99]
	global_load_dword v116, v[108:109], off
	global_load_dword v117, v[110:111], off
	global_load_dword v118, v[112:113], off
	global_load_dword v119, v[114:115], off
	s_waitcnt vmcnt(4)
	s_branch .Lp8a_pf1_done

.Lp8a_pf1_done:
	v_pk_add_f32 v[28:29], v[0:1], v[4:5]
	v_pk_add_f32 v[30:31], v[2:3], v[6:7]
	v_pk_add_f32 v[28:29], v[28:29], v[8:9]
	v_fma_f32 v35, -v33, v34, 1.0
	v_fmac_f32_e32 v34, v35, v34
	v_div_scale_f32 v35, vcc, 1.0, v32, 1.0
	v_mul_f32_e32 v36, v35, v34
	v_fma_f32 v37, -v33, v36, v35
	v_fmac_f32_e32 v36, v37, v34
	v_fma_f32 v33, -v33, v36, v35
	v_div_fmas_f32 v33, v33, v34, v36
	v_pk_add_f32 v[30:31], v[30:31], v[10:11]
	v_div_fixup_f32 v32, v33, v32, 1.0
	v_pk_add_f32 v[28:29], v[28:29], v[12:13]
	v_pk_add_f32 v[30:31], v[30:31], v[14:15]
	v_cndmask_b32_e64 v32, v103, v32, s[6:7]
	v_xor_b32_e32 v15, 0x80000000, v15
	v_xor_b32_e32 v14, 0x80000000, v14
	s_ashr_i32 s19, s18, 31
	v_pk_fma_f32 v[14:15], v[32:33], v[30:31], v[14:15] op_sel_hi:[0,1,1]
	v_pk_fma_f32 v[12:13], v[32:33], v[28:29], v[12:13] op_sel_hi:[0,1,1] neg_lo:[0,0,1] neg_hi:[0,0,1]
	s_lshl_b64 s[8:9], s[18:19], 12
	v_cvt_pk_bf16_f32 v12, v12, v13
	v_cvt_pk_bf16_f32 v13, v14, v15
	v_lshl_add_u64 v[14:15], v[88:89], 0, s[8:9]
	s_min_u32 s8, s20, 2
	s_add_i32 s8, s8, 2
	global_store_dwordx2 v[14:15], v[12:13], off
	v_cvt_f32_ubyte0_e32 v12, s8
	v_div_scale_f32 v13, s[8:9], v12, v12, 1.0
	v_rcp_f32_e32 v14, v13
	v_sub_f32_e32 v1, v17, v1
	v_sub_f32_e32 v0, v16, v0
	v_pk_add_f32 v[0:1], v[28:29], v[0:1]
	v_fma_f32 v15, -v13, v14, 1.0
	v_fmac_f32_e32 v14, v15, v14
	v_div_scale_f32 v15, vcc, 1.0, v12, 1.0
	v_mul_f32_e32 v28, v15, v14
	v_fma_f32 v29, -v13, v28, v15
	v_fmac_f32_e32 v28, v29, v14
	v_fma_f32 v13, -v13, v28, v15
	v_div_fmas_f32 v13, v13, v14, v28
	v_sub_f32_e32 v3, v19, v3
	v_sub_f32_e32 v2, v18, v2
	v_div_fixup_f32 v12, v13, v12, 1.0
	s_add_i32 s8, s18, 1
	v_pk_add_f32 v[2:3], v[30:31], v[2:3]
	v_cndmask_b32_e64 v12, v103, v12, s[6:7]
	v_xor_b32_e32 v15, 0x80000000, v19
	v_xor_b32_e32 v14, 0x80000000, v18
	s_ashr_i32 s9, s8, 31
	v_pk_fma_f32 v[14:15], v[12:13], v[2:3], v[14:15] op_sel_hi:[0,1,1]
	v_pk_fma_f32 v[12:13], v[12:13], v[0:1], v[16:17] op_sel_hi:[0,1,1] neg_lo:[0,0,1] neg_hi:[0,0,1]
	s_lshl_b64 s[8:9], s[8:9], 12
	v_cvt_pk_bf16_f32 v12, v12, v13
	v_cvt_pk_bf16_f32 v13, v14, v15
	v_lshl_add_u64 v[14:15], v[88:89], 0, s[8:9]
	s_and_b64 s[8:9], s[30:31], exec
	s_cselect_b32 s8, 3, 4
	global_store_dwordx2 v[14:15], v[12:13], off
	v_cvt_f32_ubyte0_e32 v12, s8
	v_div_scale_f32 v13, s[8:9], v12, v12, 1.0
	v_rcp_f32_e32 v14, v13
	v_sub_f32_e32 v5, v21, v5
	v_sub_f32_e32 v4, v20, v4
	v_pk_add_f32 v[0:1], v[0:1], v[4:5]
	v_fma_f32 v4, -v13, v14, 1.0
	v_fmac_f32_e32 v14, v4, v14
	v_div_scale_f32 v4, vcc, 1.0, v12, 1.0
	v_sub_f32_e32 v7, v23, v7
	v_sub_f32_e32 v6, v22, v6
	v_mul_f32_e32 v5, v4, v14
	v_pk_add_f32 v[2:3], v[2:3], v[6:7]
	v_fma_f32 v6, -v13, v5, v4
	v_fmac_f32_e32 v5, v6, v14
	v_fma_f32 v4, -v13, v5, v4
	v_div_fmas_f32 v4, v4, v14, v5
	v_div_fixup_f32 v4, v4, v12, 1.0
	s_add_i32 s8, s18, 2
	v_cndmask_b32_e64 v4, v103, v4, s[6:7]
	v_xor_b32_e32 v7, 0x80000000, v23
	v_xor_b32_e32 v6, 0x80000000, v22
	s_ashr_i32 s9, s8, 31
	v_pk_fma_f32 v[6:7], v[4:5], v[2:3], v[6:7] op_sel_hi:[0,1,1]
	v_pk_fma_f32 v[4:5], v[4:5], v[0:1], v[20:21] op_sel_hi:[0,1,1] neg_lo:[0,0,1] neg_hi:[0,0,1]
	s_lshl_b64 s[8:9], s[8:9], 12
	v_cvt_pk_bf16_f32 v4, v4, v5
	v_cvt_pk_bf16_f32 v5, v6, v7
	v_lshl_add_u64 v[6:7], v[88:89], 0, s[8:9]
	global_store_dwordx2 v[6:7], v[4:5], off
	v_sub_f32_e32 v5, v27, v11
	v_sub_f32_e32 v4, v26, v10
	v_sub_f32_e32 v7, v25, v9
	v_sub_f32_e32 v6, v24, v8
	v_pk_add_f32 v[0:1], v[0:1], v[6:7]
	v_pk_add_f32 v[2:3], v[2:3], v[4:5]
	v_xor_b32_e32 v5, 0x80000000, v27
	v_xor_b32_e32 v4, 0x80000000, v26
	v_pk_fma_f32 v[2:3], v[2:3], s[22:23], v[4:5] op_sel_hi:[1,0,1]
	v_pk_fma_f32 v[0:1], v[0:1], s[22:23], v[24:25] op_sel_hi:[1,0,1] neg_lo:[0,0,1] neg_hi:[0,0,1]
	s_or_b64 exec, exec, s[28:29]

.LBB0_1810:
	s_add_i32 s98, s2, s92
	s_cmpk_lt_i32 s98, 0x800
	s_cbranch_scc0 .Lp8a_pf2_skip
	s_add_i32 s98, s18, s24
	s_lshl_b32 s98, s98, 13
	s_mov_b32 s99, 0
	v_lshl_add_u64 v[108:109], v[86:87], 0, s[98:99]
	s_add_u32 s98, s98, 0x2000
	v_lshl_add_u64 v[110:111], v[86:87], 0, s[98:99]
	s_add_u32 s98, s98, 0x2000
	v_lshl_add_u64 v[112:113], v[86:87], 0, s[98:99]
	s_add_u32 s98, s98, 0x2000
	v_lshl_add_u64 v[114:115], v[86:87], 0, s[98:99]
	global_load_dword v116, v[108:109], off
	global_load_dword v117, v[110:111], off
	global_load_dword v118, v[112:113], off
	global_load_dword v119, v[114:115], off
	s_waitcnt vmcnt(4)
	s_branch .Lp8a_pf2_done

.Lp8a_pf2_done:
	v_pk_add_f32 v[44:45], v[0:1], v[4:5]
	s_min_u32 s8, s20, 7
	v_pk_add_f32 v[44:45], v[44:45], v[8:9]
	v_pk_add_f32 v[46:47], v[2:3], v[6:7]
	v_pk_add_f32 v[12:13], v[44:45], v[12:13]
	s_add_i32 s8, s8, 1
	v_pk_add_f32 v[46:47], v[46:47], v[10:11]
	v_pk_add_f32 v[12:13], v[12:13], v[16:17]
	v_cvt_f32_ubyte0_e32 v16, s8
	v_pk_add_f32 v[14:15], v[46:47], v[14:15]
	v_div_scale_f32 v17, s[8:9], v16, v16, 1.0
	v_pk_add_f32 v[14:15], v[14:15], v[18:19]
	v_rcp_f32_e32 v18, v17
	v_pk_add_f32 v[12:13], v[12:13], v[20:21]
	v_pk_add_f32 v[14:15], v[14:15], v[22:23]
	v_pk_add_f32 v[12:13], v[12:13], v[24:25]
	v_fma_f32 v19, -v17, v18, 1.0
	v_fmac_f32_e32 v18, v19, v18
	v_div_scale_f32 v19, vcc, 1.0, v16, 1.0
	v_mul_f32_e32 v20, v19, v18
	v_fma_f32 v21, -v17, v20, v19
	v_fmac_f32_e32 v20, v21, v18
	v_fma_f32 v17, -v17, v20, v19
	v_div_fmas_f32 v17, v17, v18, v20
	v_pk_add_f32 v[14:15], v[14:15], v[26:27]
	v_div_fixup_f32 v16, v17, v16, 1.0
	v_pk_add_f32 v[12:13], v[12:13], v[28:29]
	v_pk_add_f32 v[14:15], v[14:15], v[30:31]
	v_cndmask_b32_e64 v16, v101, v16, s[6:7]
	v_xor_b32_e32 v19, 0x80000000, v31
	v_xor_b32_e32 v18, 0x80000000, v30
	s_ashr_i32 s19, s18, 31
	v_pk_fma_f32 v[18:19], v[16:17], v[14:15], v[18:19] op_sel_hi:[0,1,1]
	v_pk_fma_f32 v[16:17], v[16:17], v[12:13], v[28:29] op_sel_hi:[0,1,1] neg_lo:[0,0,1] neg_hi:[0,0,1]
	s_lshl_b64 s[8:9], s[18:19], 12
	v_cvt_pk_bf16_f32 v16, v16, v17
	v_cvt_pk_bf16_f32 v17, v18, v19
	v_lshl_add_u64 v[18:19], v[88:89], 0, s[8:9]
	s_min_u32 s8, s20, 6
	s_add_i32 s8, s8, 2
	global_store_dwordx2 v[18:19], v[16:17], off
	v_cvt_f32_ubyte0_e32 v16, s8
	v_div_scale_f32 v17, s[8:9], v16, v16, 1.0
	v_rcp_f32_e32 v18, v17
	v_sub_f32_e32 v1, v33, v1
	v_sub_f32_e32 v0, v32, v0
	v_pk_add_f32 v[0:1], v[12:13], v[0:1]
	v_fma_f32 v12, -v17, v18, 1.0
	v_fmac_f32_e32 v18, v12, v18
	v_div_scale_f32 v12, vcc, 1.0, v16, 1.0
	v_sub_f32_e32 v3, v35, v3
	v_sub_f32_e32 v2, v34, v2
	v_mul_f32_e32 v13, v12, v18
	v_pk_add_f32 v[2:3], v[14:15], v[2:3]
	v_fma_f32 v14, -v17, v13, v12
	v_fmac_f32_e32 v13, v14, v18
	v_fma_f32 v12, -v17, v13, v12
	v_div_fmas_f32 v12, v12, v18, v13
	v_div_fixup_f32 v12, v12, v16, 1.0
	s_add_i32 s8, s18, 1
	v_cndmask_b32_e64 v12, v101, v12, s[6:7]
	v_xor_b32_e32 v15, 0x80000000, v35
	v_xor_b32_e32 v14, 0x80000000, v34
	s_ashr_i32 s9, s8, 31
	v_pk_fma_f32 v[14:15], v[12:13], v[2:3], v[14:15] op_sel_hi:[0,1,1]
	v_pk_fma_f32 v[12:13], v[12:13], v[0:1], v[32:33] op_sel_hi:[0,1,1] neg_lo:[0,0,1] neg_hi:[0,0,1]
	s_lshl_b64 s[8:9], s[8:9], 12
	v_cvt_pk_bf16_f32 v12, v12, v13
	v_cvt_pk_bf16_f32 v13, v14, v15
	v_lshl_add_u64 v[14:15], v[88:89], 0, s[8:9]
	s_min_u32 s8, s20, 5
	s_add_i32 s8, s8, 3
	global_store_dwordx2 v[14:15], v[12:13], off
	v_cvt_f32_ubyte0_e32 v12, s8
	v_div_scale_f32 v13, s[8:9], v12, v12, 1.0
	v_rcp_f32_e32 v14, v13
	v_sub_f32_e32 v5, v37, v5
	v_sub_f32_e32 v4, v36, v4
	v_pk_add_f32 v[0:1], v[0:1], v[4:5]
	v_fma_f32 v4, -v13, v14, 1.0
	v_fmac_f32_e32 v14, v4, v14
	v_div_scale_f32 v4, vcc, 1.0, v12, 1.0
	v_sub_f32_e32 v7, v39, v7
	v_sub_f32_e32 v6, v38, v6
	v_mul_f32_e32 v5, v4, v14
	v_pk_add_f32 v[2:3], v[2:3], v[6:7]
	v_fma_f32 v6, -v13, v5, v4
	v_fmac_f32_e32 v5, v6, v14
	v_fma_f32 v4, -v13, v5, v4
	v_div_fmas_f32 v4, v4, v14, v5
	v_div_fixup_f32 v4, v4, v12, 1.0
	s_add_i32 s8, s18, 2
	v_cndmask_b32_e64 v4, v101, v4, s[6:7]
	v_xor_b32_e32 v7, 0x80000000, v39
	v_xor_b32_e32 v6, 0x80000000, v38
	s_ashr_i32 s9, s8, 31
	v_pk_fma_f32 v[6:7], v[4:5], v[2:3], v[6:7] op_sel_hi:[0,1,1]
	v_pk_fma_f32 v[4:5], v[4:5], v[0:1], v[36:37] op_sel_hi:[0,1,1] neg_lo:[0,0,1] neg_hi:[0,0,1]
	s_lshl_b64 s[8:9], s[8:9], 12
	v_cvt_pk_bf16_f32 v4, v4, v5
	v_cvt_pk_bf16_f32 v5, v6, v7
	v_lshl_add_u64 v[6:7], v[88:89], 0, s[8:9]
	s_min_u32 s8, s20, 4
	s_add_i32 s8, s8, 4
	v_cvt_f32_ubyte0_e32 v12, s8
	global_store_dwordx2 v[6:7], v[4:5], off
	v_sub_f32_e32 v7, v41, v9
	v_div_scale_f32 v9, s[8:9], v12, v12, 1.0
	v_sub_f32_e32 v4, v42, v10
	v_rcp_f32_e32 v10, v9
	v_sub_f32_e32 v5, v43, v11
	v_pk_add_f32 v[2:3], v[2:3], v[4:5]
	v_sub_f32_e32 v6, v40, v8
	v_fma_f32 v4, -v9, v10, 1.0
	v_fmac_f32_e32 v10, v4, v10
	v_div_scale_f32 v4, vcc, 1.0, v12, 1.0
	v_mul_f32_e32 v5, v4, v10
	v_pk_add_f32 v[0:1], v[0:1], v[6:7]
	v_fma_f32 v6, -v9, v5, v4
	v_fmac_f32_e32 v5, v6, v10
	v_fma_f32 v4, -v9, v5, v4
	v_div_fmas_f32 v4, v4, v10, v5
	v_div_fixup_f32 v4, v4, v12, 1.0
	v_cndmask_b32_e64 v4, v101, v4, s[6:7]
	v_xor_b32_e32 v7, 0x80000000, v43
	v_xor_b32_e32 v6, 0x80000000, v42
	v_pk_fma_f32 v[2:3], v[4:5], v[2:3], v[6:7] op_sel_hi:[0,1,1]
	v_pk_fma_f32 v[0:1], v[4:5], v[0:1], v[40:41] op_sel_hi:[0,1,1] neg_lo:[0,0,1] neg_hi:[0,0,1]
	s_xor_b64 s[8:9], exec, -1

.Lp8a_pf3_done:
	v_pk_add_f32 v[104:105], v[0:1], v[4:5]
	s_min_u32 s8, s20, 15
	v_pk_add_f32 v[104:105], v[104:105], v[8:9]
	v_pk_add_f32 v[106:107], v[2:3], v[6:7]
	v_pk_add_f32 v[12:13], v[104:105], v[12:13]
	s_add_i32 s8, s8, 1
	v_pk_add_f32 v[106:107], v[106:107], v[10:11]
	v_pk_add_f32 v[12:13], v[12:13], v[16:17]
	v_cvt_f32_ubyte0_e32 v16, s8
	v_pk_add_f32 v[14:15], v[106:107], v[14:15]
	v_div_scale_f32 v17, s[8:9], v16, v16, 1.0
	v_pk_add_f32 v[14:15], v[14:15], v[18:19]
	v_rcp_f32_e32 v18, v17
	v_pk_add_f32 v[12:13], v[12:13], v[20:21]
	v_pk_add_f32 v[14:15], v[14:15], v[22:23]
	v_pk_add_f32 v[12:13], v[12:13], v[24:25]
	v_pk_add_f32 v[14:15], v[14:15], v[26:27]
	v_pk_add_f32 v[12:13], v[12:13], v[28:29]
	v_pk_add_f32 v[14:15], v[14:15], v[30:31]
	v_fma_f32 v19, -v17, v18, 1.0
	v_pk_add_f32 v[14:15], v[14:15], v[34:35]
	v_pk_add_f32 v[12:13], v[12:13], v[32:33]
	v_fmac_f32_e32 v18, v19, v18
	v_div_scale_f32 v19, vcc, 1.0, v16, 1.0
	v_pk_add_f32 v[12:13], v[12:13], v[36:37]
	v_pk_add_f32 v[14:15], v[14:15], v[38:39]
	v_mul_f32_e32 v20, v19, v18
	v_pk_add_f32 v[14:15], v[14:15], v[42:43]
	v_pk_add_f32 v[12:13], v[12:13], v[40:41]
	v_fma_f32 v21, -v17, v20, v19
	v_pk_add_f32 v[12:13], v[12:13], v[44:45]
	v_pk_add_f32 v[14:15], v[14:15], v[46:47]
	v_fmac_f32_e32 v20, v21, v18
	v_pk_add_f32 v[14:15], v[14:15], v[50:51]
	v_pk_add_f32 v[12:13], v[12:13], v[48:49]
	v_fma_f32 v17, -v17, v20, v19
	v_pk_add_f32 v[12:13], v[12:13], v[52:53]
	v_pk_add_f32 v[14:15], v[14:15], v[54:55]
	v_div_fmas_f32 v17, v17, v18, v20
	v_pk_add_f32 v[14:15], v[14:15], v[58:59]
	v_pk_add_f32 v[12:13], v[12:13], v[56:57]
	v_div_fixup_f32 v16, v17, v16, 1.0
	v_pk_add_f32 v[12:13], v[12:13], v[60:61]
	v_pk_add_f32 v[14:15], v[14:15], v[62:63]
	v_cndmask_b32_e64 v16, v102, v16, s[6:7]
	v_xor_b32_e32 v19, 0x80000000, v63
	v_xor_b32_e32 v18, 0x80000000, v62
	s_ashr_i32 s19, s18, 31
	v_pk_fma_f32 v[18:19], v[16:17], v[14:15], v[18:19] op_sel_hi:[0,1,1]
	v_pk_fma_f32 v[16:17], v[16:17], v[12:13], v[60:61] op_sel_hi:[0,1,1] neg_lo:[0,0,1] neg_hi:[0,0,1]
	s_lshl_b64 s[8:9], s[18:19], 12
	v_cvt_pk_bf16_f32 v16, v16, v17
	v_cvt_pk_bf16_f32 v17, v18, v19
	v_lshl_add_u64 v[18:19], v[88:89], 0, s[8:9]
	s_min_u32 s8, s20, 14
	s_add_i32 s8, s8, 2
	global_store_dwordx2 v[18:19], v[16:17], off
	v_cvt_f32_ubyte0_e32 v16, s8
	v_div_scale_f32 v17, s[8:9], v16, v16, 1.0
	v_rcp_f32_e32 v18, v17
	v_sub_f32_e32 v1, v65, v1
	v_sub_f32_e32 v0, v64, v0
	v_pk_add_f32 v[0:1], v[12:13], v[0:1]
	v_fma_f32 v12, -v17, v18, 1.0
	v_fmac_f32_e32 v18, v12, v18
	v_div_scale_f32 v12, vcc, 1.0, v16, 1.0
	v_sub_f32_e32 v3, v67, v3
	v_sub_f32_e32 v2, v66, v2
	v_mul_f32_e32 v13, v12, v18
	v_pk_add_f32 v[2:3], v[14:15], v[2:3]
	v_fma_f32 v14, -v17, v13, v12
	v_fmac_f32_e32 v13, v14, v18
	v_fma_f32 v12, -v17, v13, v12
	v_div_fmas_f32 v12, v12, v18, v13
	v_div_fixup_f32 v12, v12, v16, 1.0
	s_add_i32 s8, s18, 1
	v_cndmask_b32_e64 v12, v102, v12, s[6:7]
	v_xor_b32_e32 v15, 0x80000000, v67
	v_xor_b32_e32 v14, 0x80000000, v66
	s_ashr_i32 s9, s8, 31
	v_pk_fma_f32 v[14:15], v[12:13], v[2:3], v[14:15] op_sel_hi:[0,1,1]
	v_pk_fma_f32 v[12:13], v[12:13], v[0:1], v[64:65] op_sel_hi:[0,1,1] neg_lo:[0,0,1] neg_hi:[0,0,1]
	s_lshl_b64 s[8:9], s[8:9], 12
	v_cvt_pk_bf16_f32 v12, v12, v13
	v_cvt_pk_bf16_f32 v13, v14, v15
	v_lshl_add_u64 v[14:15], v[88:89], 0, s[8:9]
	s_min_u32 s8, s20, 13
	s_add_i32 s8, s8, 3
	global_store_dwordx2 v[14:15], v[12:13], off
	v_cvt_f32_ubyte0_e32 v12, s8
	v_div_scale_f32 v13, s[8:9], v12, v12, 1.0
	v_rcp_f32_e32 v14, v13
	v_sub_f32_e32 v5, v69, v5
	v_sub_f32_e32 v4, v68, v4
	v_pk_add_f32 v[0:1], v[0:1], v[4:5]
	v_fma_f32 v4, -v13, v14, 1.0
	v_fmac_f32_e32 v14, v4, v14
	v_div_scale_f32 v4, vcc, 1.0, v12, 1.0
	v_sub_f32_e32 v7, v71, v7
	v_sub_f32_e32 v6, v70, v6
	v_mul_f32_e32 v5, v4, v14
	v_pk_add_f32 v[2:3], v[2:3], v[6:7]
	v_fma_f32 v6, -v13, v5, v4
	v_fmac_f32_e32 v5, v6, v14
	v_fma_f32 v4, -v13, v5, v4
	v_div_fmas_f32 v4, v4, v14, v5
	v_div_fixup_f32 v4, v4, v12, 1.0
	s_add_i32 s8, s18, 2
	v_cndmask_b32_e64 v4, v102, v4, s[6:7]
	v_xor_b32_e32 v7, 0x80000000, v71
	v_xor_b32_e32 v6, 0x80000000, v70
	s_ashr_i32 s9, s8, 31
	v_pk_fma_f32 v[6:7], v[4:5], v[2:3], v[6:7] op_sel_hi:[0,1,1]
	v_pk_fma_f32 v[4:5], v[4:5], v[0:1], v[68:69] op_sel_hi:[0,1,1] neg_lo:[0,0,1] neg_hi:[0,0,1]
	s_lshl_b64 s[8:9], s[8:9], 12
	v_cvt_pk_bf16_f32 v4, v4, v5
	v_cvt_pk_bf16_f32 v5, v6, v7
	v_lshl_add_u64 v[6:7], v[88:89], 0, s[8:9]
	s_min_u32 s8, s20, 12
	s_add_i32 s8, s8, 4
	v_cvt_f32_ubyte0_e32 v12, s8
	global_store_dwordx2 v[6:7], v[4:5], off
	v_sub_f32_e32 v7, v73, v9
	v_div_scale_f32 v9, s[8:9], v12, v12, 1.0
	v_sub_f32_e32 v4, v74, v10
	v_rcp_f32_e32 v10, v9
	v_sub_f32_e32 v5, v75, v11
	v_pk_add_f32 v[2:3], v[2:3], v[4:5]
	v_sub_f32_e32 v6, v72, v8
	v_fma_f32 v4, -v9, v10, 1.0
	v_fmac_f32_e32 v10, v4, v10
	v_div_scale_f32 v4, vcc, 1.0, v12, 1.0
	v_mul_f32_e32 v5, v4, v10
	v_pk_add_f32 v[0:1], v[0:1], v[6:7]
	v_fma_f32 v6, -v9, v5, v4
	v_fmac_f32_e32 v5, v6, v10
	v_fma_f32 v4, -v9, v5, v4
	v_div_fmas_f32 v4, v4, v10, v5
	v_div_fixup_f32 v4, v4, v12, 1.0
	v_cndmask_b32_e64 v4, v102, v4, s[6:7]
	v_xor_b32_e32 v7, 0x80000000, v75
	v_xor_b32_e32 v6, 0x80000000, v74
	v_pk_fma_f32 v[2:3], v[4:5], v[2:3], v[6:7] op_sel_hi:[0,1,1]
	v_pk_fma_f32 v[0:1], v[4:5], v[0:1], v[72:73] op_sel_hi:[0,1,1] neg_lo:[0,0,1] neg_hi:[0,0,1]
	s_andn2_b64 s[28:29], s[28:29], exec
	s_or_b64 exec, exec, s[30:31]
	s_and_saveexec_b64 s[8:9], s[28:29]
	s_xor_b64 s[28:29], exec, s[8:9]
	s_cbranch_execnz .LBB0_1693
